# thr histogram step rewritten (first pass merges equal bins into one LDS add); attn indexer abs folded into fma, no causal compares off the diagonal
# speedup vs baseline: 1.0231x; 1.0172x over previous
; DI void dsa_thr_item(const Params& p, int b, int qblk, char* smem) {
;     ...
;       } else {
; #pragma unroll
;         for (int i = 0; i < 16; ++i) {
;           unsigned ky = fkey(sc[i]);
;           unsigned hi = (ky >> shift);
;           if ((hi >> 8) == mypref) atomicAdd(&hist[(hi & 255u) * 32 + lr], 1u);
;         }
;       }
.LBB0_271:
	s_cmp_lg_u32 s72, 0
	s_cbranch_scc1 .Lthr_h_gen
	v_lshl_add_u32 v136, v9, 7, v58
	v_mov_b32_e32 v152, 16
	v_ashrrev_i32_e32 v105, 31, v22
	v_ashrrev_i32_e32 v106, 31, v21
	v_ashrrev_i32_e32 v107, 31, v20
	v_bitop3_b32 v105, v105, v22, s67 bitop3:0x36
	v_bitop3_b32 v106, v106, v21, s67 bitop3:0x36
	v_bitop3_b32 v107, v107, v20, s67 bitop3:0x36
	v_lshrrev_b32_e32 v105, 24, v105
	v_lshrrev_b32_e32 v106, 24, v106
	v_lshrrev_b32_e32 v107, 24, v107
	v_lshl_add_u32 v137, v105, 7, v58
	v_lshl_add_u32 v138, v106, 7, v58
	v_lshl_add_u32 v139, v107, 7, v58
	v_cmp_ne_u32_e64 s[0:1], v105, v9
	v_cmp_ne_u32_e64 s[6:7], v106, v9
	v_cmp_ne_u32_e64 s[8:9], v107, v9
	v_subb_co_u32_e64 v152, s[12:13], v152, 0, s[0:1]
	v_subb_co_u32_e64 v152, s[12:13], v152, 0, s[6:7]
	v_subb_co_u32_e64 v152, s[12:13], v152, 0, s[8:9]
	s_and_saveexec_b64 s[74:75], s[0:1]
	ds_add_u32 v137, v71
	s_mov_b64 exec, s[74:75]
	s_and_saveexec_b64 s[74:75], s[6:7]
	ds_add_u32 v138, v71
	s_mov_b64 exec, s[74:75]
	s_and_saveexec_b64 s[74:75], s[8:9]
	ds_add_u32 v139, v71
	s_mov_b64 exec, s[74:75]
	v_ashrrev_i32_e32 v108, 31, v19
	v_ashrrev_i32_e32 v109, 31, v18
	v_ashrrev_i32_e32 v110, 31, v17
	v_ashrrev_i32_e32 v111, 31, v16
	v_bitop3_b32 v108, v108, v19, s67 bitop3:0x36
	v_bitop3_b32 v109, v109, v18, s67 bitop3:0x36
	v_bitop3_b32 v110, v110, v17, s67 bitop3:0x36
	v_bitop3_b32 v111, v111, v16, s67 bitop3:0x36
	v_lshrrev_b32_e32 v108, 24, v108
	v_lshrrev_b32_e32 v109, 24, v109
	v_lshrrev_b32_e32 v110, 24, v110
	v_lshrrev_b32_e32 v111, 24, v111
	v_lshl_add_u32 v140, v108, 7, v58
	v_lshl_add_u32 v141, v109, 7, v58
	v_lshl_add_u32 v142, v110, 7, v58
	v_lshl_add_u32 v143, v111, 7, v58
	v_cmp_ne_u32_e64 s[0:1], v108, v9
	v_cmp_ne_u32_e64 s[6:7], v109, v9
	v_cmp_ne_u32_e64 s[8:9], v110, v9
	v_cmp_ne_u32_e64 s[10:11], v111, v9
	v_subb_co_u32_e64 v152, s[12:13], v152, 0, s[0:1]
	v_subb_co_u32_e64 v152, s[12:13], v152, 0, s[6:7]
	v_subb_co_u32_e64 v152, s[12:13], v152, 0, s[8:9]
	v_subb_co_u32_e64 v152, s[12:13], v152, 0, s[10:11]
	s_and_saveexec_b64 s[74:75], s[0:1]
	ds_add_u32 v140, v71
	s_mov_b64 exec, s[74:75]
	s_and_saveexec_b64 s[74:75], s[6:7]
	ds_add_u32 v141, v71
	s_mov_b64 exec, s[74:75]
	s_and_saveexec_b64 s[74:75], s[8:9]
	ds_add_u32 v142, v71
	s_mov_b64 exec, s[74:75]
	s_and_saveexec_b64 s[74:75], s[10:11]
	ds_add_u32 v143, v71
	s_mov_b64 exec, s[74:75]
	v_ashrrev_i32_e32 v112, 31, v7
	v_ashrrev_i32_e32 v113, 31, v6
	v_ashrrev_i32_e32 v114, 31, v5
	v_ashrrev_i32_e32 v115, 31, v4
	v_bitop3_b32 v112, v112, v7, s67 bitop3:0x36
	v_bitop3_b32 v113, v113, v6, s67 bitop3:0x36
	v_bitop3_b32 v114, v114, v5, s67 bitop3:0x36
	v_bitop3_b32 v115, v115, v4, s67 bitop3:0x36
	v_lshrrev_b32_e32 v112, 24, v112
	v_lshrrev_b32_e32 v113, 24, v113
	v_lshrrev_b32_e32 v114, 24, v114
	v_lshrrev_b32_e32 v115, 24, v115
	v_lshl_add_u32 v144, v112, 7, v58
	v_lshl_add_u32 v145, v113, 7, v58
	v_lshl_add_u32 v146, v114, 7, v58
	v_lshl_add_u32 v147, v115, 7, v58
	v_cmp_ne_u32_e64 s[0:1], v112, v9
	v_cmp_ne_u32_e64 s[6:7], v113, v9
	v_cmp_ne_u32_e64 s[8:9], v114, v9
	v_cmp_ne_u32_e64 s[10:11], v115, v9
	v_subb_co_u32_e64 v152, s[12:13], v152, 0, s[0:1]
	v_subb_co_u32_e64 v152, s[12:13], v152, 0, s[6:7]
	v_subb_co_u32_e64 v152, s[12:13], v152, 0, s[8:9]
	v_subb_co_u32_e64 v152, s[12:13], v152, 0, s[10:11]
	s_and_saveexec_b64 s[74:75], s[0:1]
	ds_add_u32 v144, v71
	s_mov_b64 exec, s[74:75]
	s_and_saveexec_b64 s[74:75], s[6:7]
	ds_add_u32 v145, v71
	s_mov_b64 exec, s[74:75]
	s_and_saveexec_b64 s[74:75], s[8:9]
	ds_add_u32 v146, v71
	s_mov_b64 exec, s[74:75]
	s_and_saveexec_b64 s[74:75], s[10:11]
	ds_add_u32 v147, v71
	s_mov_b64 exec, s[74:75]
	v_ashrrev_i32_e32 v116, 31, v3
	v_ashrrev_i32_e32 v117, 31, v2
	v_ashrrev_i32_e32 v118, 31, v1
	v_ashrrev_i32_e32 v119, 31, v0
	v_bitop3_b32 v116, v116, v3, s67 bitop3:0x36
	v_bitop3_b32 v117, v117, v2, s67 bitop3:0x36
	v_bitop3_b32 v118, v118, v1, s67 bitop3:0x36
	v_bitop3_b32 v119, v119, v0, s67 bitop3:0x36
	v_lshrrev_b32_e32 v116, 24, v116
	v_lshrrev_b32_e32 v117, 24, v117
	v_lshrrev_b32_e32 v118, 24, v118
	v_lshrrev_b32_e32 v119, 24, v119
	v_lshl_add_u32 v148, v116, 7, v58
	v_lshl_add_u32 v149, v117, 7, v58
	v_lshl_add_u32 v150, v118, 7, v58
	v_lshl_add_u32 v151, v119, 7, v58
	v_cmp_ne_u32_e64 s[0:1], v116, v9
	v_cmp_ne_u32_e64 s[6:7], v117, v9
	v_cmp_ne_u32_e64 s[8:9], v118, v9
	v_cmp_ne_u32_e64 s[10:11], v119, v9
	v_subb_co_u32_e64 v152, s[12:13], v152, 0, s[0:1]
	v_subb_co_u32_e64 v152, s[12:13], v152, 0, s[6:7]
	v_subb_co_u32_e64 v152, s[12:13], v152, 0, s[8:9]
	v_subb_co_u32_e64 v152, s[12:13], v152, 0, s[10:11]
	s_and_saveexec_b64 s[74:75], s[0:1]
	ds_add_u32 v148, v71
	s_mov_b64 exec, s[74:75]
	s_and_saveexec_b64 s[74:75], s[6:7]
	ds_add_u32 v149, v71
	s_mov_b64 exec, s[74:75]
	s_and_saveexec_b64 s[74:75], s[8:9]
	ds_add_u32 v150, v71
	s_mov_b64 exec, s[74:75]
	s_and_saveexec_b64 s[74:75], s[10:11]
	ds_add_u32 v151, v71
	s_mov_b64 exec, s[74:75]
	ds_add_u32 v136, v152
	s_branch .Lthr_h_done
; DI void dsa_thr_item(const Params& p, int b, int qblk, char* smem) {
;     ...
;     const int shift = 24 - 8 * pass;
;     const unsigned mypref = pref[lr];
;     ...
;       } else {
; #pragma unroll
;         for (int i = 0; i < 16; ++i) {
;           unsigned ky = fkey(sc[i]);
;           unsigned hi = (ky >> shift);
;           if ((hi >> 8) == mypref) atomicAdd(&hist[(hi & 255u) * 32 + lr], 1u);
;         }
;       }
.Lthr_h_gen:
	s_add_i32 s62, s58, 8
	v_lshrrev_b32_e32 v120, 8, v9
	v_and_b32_e32 v104, 0xff, v9
	v_ashrrev_i32_e32 v105, 31, v22
	v_ashrrev_i32_e32 v106, 31, v21
	v_ashrrev_i32_e32 v107, 31, v20
	v_bitop3_b32 v105, v105, v22, s67 bitop3:0x36
	v_bitop3_b32 v106, v106, v21, s67 bitop3:0x36
	v_bitop3_b32 v107, v107, v20, s67 bitop3:0x36
	v_lshrrev_b32_e32 v121, s62, v105
	v_lshrrev_b32_e32 v122, s62, v106
	v_lshrrev_b32_e32 v123, s62, v107
	v_bfe_u32 v105, v105, s58, 8
	v_bfe_u32 v106, v106, s58, 8
	v_bfe_u32 v107, v107, s58, 8
	v_cmp_eq_u32_e64 s[0:1], v120, v94
	v_cmp_eq_u32_e64 s[6:7], v121, v94
	v_cmp_eq_u32_e64 s[8:9], v122, v94
	v_cmp_eq_u32_e64 s[10:11], v123, v94
	v_lshl_add_u32 v136, v104, 7, v58
	v_lshl_add_u32 v137, v105, 7, v58
	v_lshl_add_u32 v138, v106, 7, v58
	v_lshl_add_u32 v139, v107, 7, v58
	s_and_saveexec_b64 s[74:75], s[0:1]
	ds_add_u32 v136, v71
	s_mov_b64 exec, s[74:75]
	s_and_saveexec_b64 s[74:75], s[6:7]
	ds_add_u32 v137, v71
	s_mov_b64 exec, s[74:75]
	s_and_saveexec_b64 s[74:75], s[8:9]
	ds_add_u32 v138, v71
	s_mov_b64 exec, s[74:75]
	s_and_saveexec_b64 s[74:75], s[10:11]
	ds_add_u32 v139, v71
	s_mov_b64 exec, s[74:75]
	v_ashrrev_i32_e32 v108, 31, v19
	v_ashrrev_i32_e32 v109, 31, v18
	v_ashrrev_i32_e32 v110, 31, v17
	v_ashrrev_i32_e32 v111, 31, v16
	v_bitop3_b32 v108, v108, v19, s67 bitop3:0x36
	v_bitop3_b32 v109, v109, v18, s67 bitop3:0x36
	v_bitop3_b32 v110, v110, v17, s67 bitop3:0x36
	v_bitop3_b32 v111, v111, v16, s67 bitop3:0x36
	v_lshrrev_b32_e32 v124, s62, v108
	v_lshrrev_b32_e32 v125, s62, v109
	v_lshrrev_b32_e32 v126, s62, v110
	v_lshrrev_b32_e32 v127, s62, v111
	v_bfe_u32 v108, v108, s58, 8
	v_bfe_u32 v109, v109, s58, 8
	v_bfe_u32 v110, v110, s58, 8
	v_bfe_u32 v111, v111, s58, 8
	v_cmp_eq_u32_e64 s[0:1], v124, v94
	v_cmp_eq_u32_e64 s[6:7], v125, v94
	v_cmp_eq_u32_e64 s[8:9], v126, v94
	v_cmp_eq_u32_e64 s[10:11], v127, v94
	v_lshl_add_u32 v140, v108, 7, v58
	v_lshl_add_u32 v141, v109, 7, v58
	v_lshl_add_u32 v142, v110, 7, v58
	v_lshl_add_u32 v143, v111, 7, v58
	s_and_saveexec_b64 s[74:75], s[0:1]
	ds_add_u32 v140, v71
	s_mov_b64 exec, s[74:75]
	s_and_saveexec_b64 s[74:75], s[6:7]
	ds_add_u32 v141, v71
	s_mov_b64 exec, s[74:75]
	s_and_saveexec_b64 s[74:75], s[8:9]
	ds_add_u32 v142, v71
	s_mov_b64 exec, s[74:75]
	s_and_saveexec_b64 s[74:75], s[10:11]
	ds_add_u32 v143, v71
	s_mov_b64 exec, s[74:75]
	v_ashrrev_i32_e32 v112, 31, v7
	v_ashrrev_i32_e32 v113, 31, v6
	v_ashrrev_i32_e32 v114, 31, v5
	v_ashrrev_i32_e32 v115, 31, v4
	v_bitop3_b32 v112, v112, v7, s67 bitop3:0x36
	v_bitop3_b32 v113, v113, v6, s67 bitop3:0x36
	v_bitop3_b32 v114, v114, v5, s67 bitop3:0x36
	v_bitop3_b32 v115, v115, v4, s67 bitop3:0x36
	v_lshrrev_b32_e32 v128, s62, v112
	v_lshrrev_b32_e32 v129, s62, v113
	v_lshrrev_b32_e32 v130, s62, v114
	v_lshrrev_b32_e32 v131, s62, v115
	v_bfe_u32 v112, v112, s58, 8
	v_bfe_u32 v113, v113, s58, 8
	v_bfe_u32 v114, v114, s58, 8
	v_bfe_u32 v115, v115, s58, 8
	v_cmp_eq_u32_e64 s[0:1], v128, v94
	v_cmp_eq_u32_e64 s[6:7], v129, v94
	v_cmp_eq_u32_e64 s[8:9], v130, v94
	v_cmp_eq_u32_e64 s[10:11], v131, v94
	v_lshl_add_u32 v144, v112, 7, v58
	v_lshl_add_u32 v145, v113, 7, v58
	v_lshl_add_u32 v146, v114, 7, v58
	v_lshl_add_u32 v147, v115, 7, v58
	s_and_saveexec_b64 s[74:75], s[0:1]
	ds_add_u32 v144, v71
	s_mov_b64 exec, s[74:75]
	s_and_saveexec_b64 s[74:75], s[6:7]
	ds_add_u32 v145, v71
	s_mov_b64 exec, s[74:75]
	s_and_saveexec_b64 s[74:75], s[8:9]
	ds_add_u32 v146, v71
	s_mov_b64 exec, s[74:75]
	s_and_saveexec_b64 s[74:75], s[10:11]
	ds_add_u32 v147, v71
	s_mov_b64 exec, s[74:75]
	v_ashrrev_i32_e32 v116, 31, v3
	v_ashrrev_i32_e32 v117, 31, v2
	v_ashrrev_i32_e32 v118, 31, v1
	v_ashrrev_i32_e32 v119, 31, v0
	v_bitop3_b32 v116, v116, v3, s67 bitop3:0x36
	v_bitop3_b32 v117, v117, v2, s67 bitop3:0x36
	v_bitop3_b32 v118, v118, v1, s67 bitop3:0x36
	v_bitop3_b32 v119, v119, v0, s67 bitop3:0x36
	v_lshrrev_b32_e32 v132, s62, v116
	v_lshrrev_b32_e32 v133, s62, v117
	v_lshrrev_b32_e32 v134, s62, v118
	v_lshrrev_b32_e32 v135, s62, v119
	v_bfe_u32 v116, v116, s58, 8
	v_bfe_u32 v117, v117, s58, 8
	v_bfe_u32 v118, v118, s58, 8
	v_bfe_u32 v119, v119, s58, 8
	v_cmp_eq_u32_e64 s[0:1], v132, v94
	v_cmp_eq_u32_e64 s[6:7], v133, v94
	v_cmp_eq_u32_e64 s[8:9], v134, v94
	v_cmp_eq_u32_e64 s[10:11], v135, v94
	v_lshl_add_u32 v148, v116, 7, v58
	v_lshl_add_u32 v149, v117, 7, v58
	v_lshl_add_u32 v150, v118, 7, v58
	v_lshl_add_u32 v151, v119, 7, v58
	s_and_saveexec_b64 s[74:75], s[0:1]
	ds_add_u32 v148, v71
	s_mov_b64 exec, s[74:75]
	s_and_saveexec_b64 s[74:75], s[6:7]
	ds_add_u32 v149, v71
	s_mov_b64 exec, s[74:75]
	s_and_saveexec_b64 s[74:75], s[8:9]
	ds_add_u32 v150, v71
	s_mov_b64 exec, s[74:75]
	s_and_saveexec_b64 s[74:75], s[10:11]
	ds_add_u32 v151, v71
	s_mov_b64 exec, s[74:75]
.Lthr_h_done:
	s_mov_b64 s[62:63], 0
	s_andn2_saveexec_b64 s[64:65], s[64:65]
	s_cbranch_execz .LBB0_270

; #define MFMA(a, b, c) __builtin_amdgcn_mfma_f32_32x32x16_bf16((a), (b), (c), 0, 0, 0)
; DI int crow(int i, int h) { return (i & 3) + 8 * (i >> 2) + 4 * h; }
; DI f32x16 zero16() { f32x16 z; for (int i = 0; i < 16; ++i) z[i] = 0.f; return z; }
; DI void dsa_attn_item(const Params& p, int b, int qblk, char* smem) {
;     ...
; #pragma unroll 2
;         for (int hd = 0; hd < 8; ++hd) {
;           f32x16 a = zero16();
;           a = MFMA(k0, *reinterpret_cast<const bf16x8*>(qil + hd * 32), a);
;           a = MFMA(k1, *reinterpret_cast<const bf16x8*>(qil + hd * 32 + 16), a);
;           const float wh = wqs[hd * 32 + lr];
; #pragma unroll
;           for (int i = 0; i < 16; ++i) sc[i] = fmaf(fabsf(a[i]), wh, sc[i]);
;         }
;         __builtin_amdgcn_sched_barrier(0);
; #pragma unroll
;         for (int i = 0; i < 16; ++i) {
;           int kp = key0 + crow(i, lh);
;           if (kp <= q0 + lr && fkey(sc[i]) >= thrq) bits |= (1u << i);
;         }
.LBB0_436:
	v_add_u32_e32 v70, s0, v219
	ds_read_b128 v[50:53], v70
	ds_read_b128 v[230:233], v70 offset:32
	ds_read_b128 v[66:69], v70 offset:64
	ds_read_b128 v[234:237], v70 offset:96
	s_addk_i32 s0, 0x80
	s_cmpk_eq_i32 s0, 0x200
	s_waitcnt lgkmcnt(3)
	v_mfma_f32_32x32x16_bf16 v[50:65], v[154:157], v[50:53], 0
	s_waitcnt lgkmcnt(1)
	v_mfma_f32_32x32x16_bf16 v[66:81], v[154:157], v[66:69], 0
	v_mfma_f32_32x32x16_bf16 v[50:65], v[158:161], v[230:233], v[50:65]
	ds_read2_b32 v[230:231], v195 offset1:32
	v_add_u32_e32 v195, 0x100, v195
	s_waitcnt lgkmcnt(0)
	v_mov_b32_e32 v232, v231
	v_mfma_f32_32x32x16_bf16 v[66:81], v[158:161], v[234:237], v[66:81]
	s_nop 6
	v_fma_f32 v34, |v50|, v230, v34
	v_fma_f32 v35, |v51|, v230, v35
	v_fma_f32 v36, |v52|, v230, v36
	v_fma_f32 v37, |v53|, v230, v37
	v_fma_f32 v38, |v54|, v230, v38
	v_fma_f32 v39, |v55|, v230, v39
	v_fma_f32 v40, |v56|, v230, v40
	v_fma_f32 v41, |v57|, v230, v41
	v_fma_f32 v42, |v58|, v230, v42
	v_fma_f32 v43, |v59|, v230, v43
	v_fma_f32 v44, |v60|, v230, v44
	v_fma_f32 v45, |v61|, v230, v45
	v_fma_f32 v46, |v62|, v230, v46
	v_fma_f32 v47, |v63|, v230, v47
	v_fma_f32 v48, |v64|, v230, v48
	v_fma_f32 v49, |v65|, v230, v49
	v_fma_f32 v34, |v66|, v232, v34
	v_fma_f32 v35, |v67|, v232, v35
	v_fma_f32 v36, |v68|, v232, v36
	v_fma_f32 v37, |v69|, v232, v37
	v_fma_f32 v38, |v70|, v232, v38
	v_fma_f32 v39, |v71|, v232, v39
	v_fma_f32 v40, |v72|, v232, v40
	v_fma_f32 v41, |v73|, v232, v41
	v_fma_f32 v42, |v74|, v232, v42
	v_fma_f32 v43, |v75|, v232, v43
	v_fma_f32 v44, |v76|, v232, v44
	v_fma_f32 v45, |v77|, v232, v45
	v_fma_f32 v46, |v78|, v232, v46
	v_fma_f32 v47, |v79|, v232, v47
	v_fma_f32 v48, |v80|, v232, v48
	v_fma_f32 v49, |v81|, v232, v49
	s_cbranch_scc0 .LBB0_436
	v_readfirstlane_b32 s0, v167
	s_add_i32 s0, s0, s40
	s_cmp_lt_u32 s0, s52
	s_cbranch_scc0 .Lattn_mg_diag
	v_ashrrev_i32_e32 v50, 31, v34
	v_ashrrev_i32_e32 v51, 31, v35
	v_ashrrev_i32_e32 v52, 31, v36
	v_ashrrev_i32_e32 v53, 31, v37
	v_bitop3_b32 v50, v50, v34, s49 bitop3:0x36
	v_bitop3_b32 v51, v51, v35, s49 bitop3:0x36
	v_bitop3_b32 v52, v52, v36, s49 bitop3:0x36
	v_bitop3_b32 v53, v53, v37, s49 bitop3:0x36
	v_cmp_lt_u32_e64 s[0:1], v50, v82
	v_cmp_lt_u32_e64 s[6:7], v51, v82
	v_cmp_lt_u32_e64 s[10:11], v52, v82
	v_cmp_lt_u32_e64 s[12:13], v53, v82
	v_cndmask_b32_e64 v66, 0, v254, s[0:1]
	v_cndmask_b32_e64 v67, 0, v254, s[6:7]
	v_cndmask_b32_e64 v68, 0, v254, s[10:11]
	v_cndmask_b32_e64 v69, 0, v254, s[12:13]
	v_ashrrev_i32_e32 v54, 31, v38
	v_ashrrev_i32_e32 v55, 31, v39
	v_ashrrev_i32_e32 v56, 31, v40
	v_ashrrev_i32_e32 v57, 31, v41
	v_bitop3_b32 v54, v54, v38, s49 bitop3:0x36
	v_bitop3_b32 v55, v55, v39, s49 bitop3:0x36
	v_bitop3_b32 v56, v56, v40, s49 bitop3:0x36
	v_bitop3_b32 v57, v57, v41, s49 bitop3:0x36
	v_cmp_lt_u32_e64 s[0:1], v54, v82
	v_cmp_lt_u32_e64 s[6:7], v55, v82
	v_cmp_lt_u32_e64 s[10:11], v56, v82
	v_cmp_lt_u32_e64 s[12:13], v57, v82
	v_cndmask_b32_e64 v70, 0, v254, s[0:1]
	v_cndmask_b32_e64 v71, 0, v254, s[6:7]
	v_cndmask_b32_e64 v72, 0, v254, s[10:11]
	v_cndmask_b32_e64 v73, 0, v254, s[12:13]
	v_ashrrev_i32_e32 v58, 31, v42
	v_ashrrev_i32_e32 v59, 31, v43
	v_ashrrev_i32_e32 v60, 31, v44
	v_ashrrev_i32_e32 v61, 31, v45
	v_bitop3_b32 v58, v58, v42, s49 bitop3:0x36
	v_bitop3_b32 v59, v59, v43, s49 bitop3:0x36
	v_bitop3_b32 v60, v60, v44, s49 bitop3:0x36
	v_bitop3_b32 v61, v61, v45, s49 bitop3:0x36
	v_cmp_lt_u32_e64 s[0:1], v58, v82
	v_cmp_lt_u32_e64 s[6:7], v59, v82
	v_cmp_lt_u32_e64 s[10:11], v60, v82
	v_cmp_lt_u32_e64 s[12:13], v61, v82
	v_cndmask_b32_e64 v74, 0, v254, s[0:1]
	v_cndmask_b32_e64 v75, 0, v254, s[6:7]
	v_cndmask_b32_e64 v76, 0, v254, s[10:11]
	v_cndmask_b32_e64 v77, 0, v254, s[12:13]
	v_ashrrev_i32_e32 v62, 31, v46
	v_ashrrev_i32_e32 v63, 31, v47
	v_ashrrev_i32_e32 v64, 31, v48
	v_ashrrev_i32_e32 v65, 31, v49
	v_bitop3_b32 v62, v62, v46, s49 bitop3:0x36
	v_bitop3_b32 v63, v63, v47, s49 bitop3:0x36
	v_bitop3_b32 v64, v64, v48, s49 bitop3:0x36
	v_bitop3_b32 v65, v65, v49, s49 bitop3:0x36
	v_cmp_lt_u32_e64 s[0:1], v62, v82
	v_cmp_lt_u32_e64 s[6:7], v63, v82
	v_cmp_lt_u32_e64 s[10:11], v64, v82
	v_cmp_lt_u32_e64 s[12:13], v65, v82
	v_cndmask_b32_e64 v78, 0, v254, s[0:1]
	v_cndmask_b32_e64 v79, 0, v254, s[6:7]
	v_cndmask_b32_e64 v80, 0, v254, s[10:11]
	v_cndmask_b32_e64 v81, 0, v254, s[12:13]
	s_branch .Lattn_mg_tail
; DI int crow(int i, int h) { return (i & 3) + 8 * (i >> 2) + 4 * h; }
; DI void dsa_attn_item(const Params& p, int b, int qblk, char* smem) {
;     ...
; #pragma unroll
;         for (int i = 0; i < 16; ++i) {
;           int kp = key0 + crow(i, lh);
;           if (kp <= q0 + lr && fkey(sc[i]) >= thrq) bits |= (1u << i);
;         }
;       }
;       maskbuf[(buf * 8 + wave) * 64 + lane] = (u16)bits;
.Lattn_mg_diag:
	v_or_b32_e32 v0, v0, v214
	v_ashrrev_i32_e32 v50, 31, v34
	v_bitop3_b32 v34, v50, v34, s49 bitop3:0x36
	v_ashrrev_i32_e32 v50, 31, v35
	v_or_b32_e32 v51, 16, v0
	v_cmp_le_u32_e32 vcc, v0, v84
	v_cmp_ge_u32_e64 s[0:1], v34, v82
	v_bitop3_b32 v35, v50, v35, s49 bitop3:0x36
	v_or_b32_e32 v52, 2, v0
	v_cmp_gt_u32_e64 s[16:17], v51, v90
	v_ashrrev_i32_e32 v51, 31, v37
	s_and_b64 s[0:1], vcc, s[0:1]
	v_cmp_lt_u32_e32 vcc, v35, v82
	v_or_b32_e32 v53, 10, v0
	v_or_b32_e32 v56, 3, v0
	v_cmp_gt_u32_e64 s[14:15], v52, v84
	v_ashrrev_i32_e32 v52, 31, v43
	v_bitop3_b32 v37, v51, v37, s49 bitop3:0x36
	v_cndmask_b32_e64 v66, v254, 0, s[0:1]
	v_cndmask_b32_e64 v67, 0, v254, vcc
	v_cmp_lt_u32_e32 vcc, v0, v84
	v_or_b32_e32 v54, 9, v0
	v_or_b32_e32 v55, 17, v0
	v_or_b32_e32 v57, 11, v0
	v_cmp_gt_u32_e64 s[0:1], v56, v83
	v_cmp_gt_u32_e64 s[12:13], v53, v88
	v_ashrrev_i32_e32 v53, 31, v39
	v_bitop3_b32 v43, v52, v43, s49 bitop3:0x36
	v_cmp_lt_u32_e64 s[22:23], v37, v91
	v_cndmask_b32_e32 v67, v254, v67, vcc
	v_cmp_gt_u32_e32 vcc, v57, v87
	v_cmp_gt_u32_e64 s[6:7], v55, v89
	v_cmp_gt_u32_e64 s[10:11], v54, v85
	v_ashrrev_i32_e32 v54, 31, v40
	v_ashrrev_i32_e32 v57, 31, v38
	v_bitop3_b32 v39, v53, v39, s49 bitop3:0x36
	v_cmp_lt_u32_e64 s[24:25], v43, v97
	s_or_b64 s[0:1], s[0:1], s[22:23]
	v_ashrrev_i32_e32 v55, 31, v36
	v_bitop3_b32 v38, v57, v38, s49 bitop3:0x36
	v_bitop3_b32 v40, v54, v40, s49 bitop3:0x36
	v_cmp_lt_u32_e64 s[26:27], v39, v93
	v_cndmask_b32_e64 v69, 0, v254, s[0:1]
	s_or_b64 s[0:1], s[6:7], s[24:25]
	v_or_b32_e32 v50, 8, v0
	v_ashrrev_i32_e32 v56, 31, v42
	v_bitop3_b32 v36, v55, v36, s49 bitop3:0x36
	v_cmp_lt_u32_e64 s[28:29], v40, v94
	v_cmp_lt_u32_e64 s[36:37], v38, v92
	v_cndmask_b32_e64 v75, 0, v254, s[0:1]
	s_or_b64 s[0:1], s[10:11], s[26:27]
	v_cmp_gt_u32_e64 s[18:19], v50, v86
	v_ashrrev_i32_e32 v50, 31, v41
	v_bitop3_b32 v42, v56, v42, s49 bitop3:0x36
	v_cmp_lt_u32_e64 s[30:31], v36, v82
	v_cndmask_b32_e64 v71, 0, v254, s[0:1]
	s_or_b64 s[0:1], s[12:13], s[28:29]
	v_bitop3_b32 v41, v50, v41, s49 bitop3:0x36
	v_cmp_lt_u32_e64 s[34:35], v42, v96
	v_cndmask_b32_e64 v72, 0, v254, s[0:1]
	s_or_b64 s[0:1], s[14:15], s[30:31]
	v_cmp_lt_u32_e64 s[20:21], v41, v95
	v_cndmask_b32_e64 v68, 0, v254, s[0:1]
	s_or_b64 s[0:1], s[16:17], s[34:35]
	v_or_b32_e32 v50, 18, v0
	s_or_b64 s[20:21], vcc, s[20:21]
	v_cndmask_b32_e64 v74, 0, v254, s[0:1]
	s_or_b64 s[0:1], s[18:19], s[36:37]
	v_cmp_gt_u32_e32 vcc, v50, v84
	v_or_b32_e32 v50, 19, v0
	v_cndmask_b32_e64 v70, 0, v254, s[0:1]
	v_cmp_gt_u32_e64 s[0:1], v50, v84
	v_ashrrev_i32_e32 v50, 31, v45
	v_ashrrev_i32_e32 v51, 31, v44
	v_or_b32_e32 v50, 0x80000000, v50
	v_or_b32_e32 v51, 0x80000000, v51
	v_xor_b32_e32 v45, v50, v45
	v_xor_b32_e32 v44, v51, v44
	v_cmp_lt_u32_e64 s[6:7], v45, v163
	v_cmp_lt_u32_e64 s[10:11], v44, v204
	v_or_b32_e32 v50, 24, v0
	s_or_b64 s[10:11], vcc, s[10:11]
	s_or_b64 s[0:1], s[0:1], s[6:7]
	v_cmp_gt_u32_e32 vcc, v50, v84
	v_or_b32_e32 v50, 25, v0
	v_cndmask_b32_e64 v77, 0, v254, s[0:1]
	v_cmp_gt_u32_e64 s[0:1], v50, v84
	v_ashrrev_i32_e32 v50, 31, v47
	v_ashrrev_i32_e32 v51, 31, v46
	v_or_b32_e32 v50, 0x80000000, v50
	v_or_b32_e32 v51, 0x80000000, v51
	v_xor_b32_e32 v47, v50, v47
	v_xor_b32_e32 v46, v51, v46
	v_cmp_lt_u32_e64 s[6:7], v47, v163
	v_cndmask_b32_e64 v76, 0, v254, s[10:11]
	v_cmp_lt_u32_e64 s[10:11], v46, v204
	s_or_b64 s[0:1], s[0:1], s[6:7]
	v_or_b32_e32 v50, 26, v0
	v_or_b32_e32 v0, 27, v0
	s_or_b64 s[10:11], vcc, s[10:11]
	v_cndmask_b32_e64 v79, 0, v254, s[0:1]
	v_cmp_gt_u32_e32 vcc, v50, v84
	v_cmp_gt_u32_e64 s[0:1], v0, v84
	v_ashrrev_i32_e32 v0, 31, v49
	v_ashrrev_i32_e32 v50, 31, v48
	v_or_b32_e32 v0, 0x80000000, v0
	v_or_b32_e32 v50, 0x80000000, v50
	v_xor_b32_e32 v0, v0, v49
	v_xor_b32_e32 v48, v50, v48
	v_cndmask_b32_e64 v78, 0, v254, s[10:11]
	v_cmp_lt_u32_e64 s[6:7], v0, v163
	v_cmp_lt_u32_e64 s[10:11], v48, v204
	v_cndmask_b32_e64 v73, 0, v254, s[20:21]
	s_or_b64 s[10:11], vcc, s[10:11]
	s_or_b64 s[0:1], s[0:1], s[6:7]
	v_cndmask_b32_e64 v80, 0, v254, s[10:11]
	v_cndmask_b32_e64 v81, 0, v254, s[0:1]
.Lattn_mg_tail:
	s_and_b32 s0, s40, 8
	v_add_u32_e32 v50, s0, v167
	v_lshl_add_u32 v50, v50, 12, v164
	v_add_u32_e32 v50, 0x10000, v50
	ds_write_b128 v50, v[66:69]
	ds_write_b128 v50, v[70:73] offset:1024
	ds_write_b128 v50, v[74:77] offset:2048
	ds_write_b128 v50, v[78:81] offset:3072
